# EpiResid (P2/P8/P10): second half's residual tile loads issued with the first half's
# baseline (speedup 1.0000x reference)
.LBB0_432:
	v_mov_b32_e32 v130, v187
	v_mov_b32_e32 v131, v186
	s_lshl_b32 s22, s35, 8
	s_add_i32 s22, s22, s80
	v_and_b32_e32 v132, 64, v225
	v_add_u32_e32 v170, s22, v130
	s_lshl_b32 s22, s44, 8
	v_xor_b32_e32 v130, 16, v225
	v_add_u32_e32 v132, 64, v132
	s_or_b32 s22, s22, s81
	v_cmp_lt_i32_e32 vcc, v130, v132
	v_lshl_add_u32 v168, v131, 3, s22
	v_ashrrev_i32_e32 v169, 31, v168
	v_cndmask_b32_e32 v130, v225, v130, vcc
	v_lshlrev_b32_e32 v190, 2, v130
	v_xor_b32_e32 v130, 32, v225
	v_cmp_lt_i32_e32 vcc, v130, v132
	v_lshlrev_b64 v[196:197], 1, v[168:169]
	v_ashrrev_i32_e32 v171, 31, v170
	v_cndmask_b32_e32 v130, v225, v130, vcc
	v_lshl_add_u64 v[172:173], s[50:51], 0, v[196:197]
	v_lshlrev_b64 v[198:199], 11, v[170:171]
	v_lshlrev_b32_e32 v191, 2, v130
	v_cmp_eq_u32_e32 vcc, 0, v131
	v_lshl_add_u64 v[130:131], v[172:173], 0, v[198:199]
	global_load_dwordx4 v[192:195], v[130:131], off
	global_load_dwordx4 v[154:157], v[130:131], off offset:256
	v_add_u32_e32 v182, 16, v170
	v_ashrrev_i32_e32 v183, 31, v182
	v_add_u32_e32 v178, 32, v170
	v_lshlrev_b64 v[184:185], 11, v[182:183]
	v_ashrrev_i32_e32 v179, 31, v178
	v_add_u32_e32 v174, 48, v170
	v_lshl_add_u64 v[130:131], v[172:173], 0, v[184:185]
	v_lshlrev_b64 v[180:181], 11, v[178:179]
	v_ashrrev_i32_e32 v175, 31, v174
	global_load_dwordx4 v[150:153], v[130:131], off
	global_load_dwordx4 v[146:149], v[130:131], off offset:256
	v_lshl_add_u64 v[130:131], v[172:173], 0, v[180:181]
	v_lshlrev_b64 v[176:177], 11, v[174:175]
	global_load_dwordx4 v[142:145], v[130:131], off
	global_load_dwordx4 v[138:141], v[130:131], off offset:256
	v_lshl_add_u64 v[130:131], v[172:173], 0, v[176:177]
	global_load_dwordx4 v[134:137], v[130:131], off
	s_nop 0
	global_load_dwordx4 v[130:133], v[130:131], off offset:256
	s_mov_b64 s[22:23], 0x40000
	v_lshl_add_u64 v[218:219], v[172:173], 0, v[198:199]
	v_lshl_add_u64 v[218:219], s[22:23], 0, v[218:219]
	global_load_dwordx4 v[202:205], v[218:219], off
	global_load_dwordx4 v[206:209], v[218:219], off offset:256
	v_lshl_add_u64 v[218:219], v[172:173], 0, v[184:185]
	v_lshl_add_u64 v[218:219], s[22:23], 0, v[218:219]
	global_load_dwordx4 v[210:213], v[218:219], off
	global_load_dwordx4 v[214:217], v[218:219], off offset:256
	v_lshl_add_u64 v[218:219], v[172:173], 0, v[180:181]
	v_lshl_add_u64 v[218:219], s[22:23], 0, v[218:219]
	global_load_dwordx4 v[236:239], v[218:219], off
	global_load_dwordx4 v[240:243], v[218:219], off offset:256
	v_lshl_add_u64 v[218:219], v[172:173], 0, v[176:177]
	v_lshl_add_u64 v[218:219], s[22:23], 0, v[218:219]
	global_load_dwordx4 v[244:247], v[218:219], off
	global_load_dwordx4 v[158:161], v[218:219], off offset:256
	s_waitcnt vmcnt(0)
	v_lshlrev_b32_e32 v200, 16, v192
	v_and_b32_e32 v201, 0xffff0000, v192
	v_lshlrev_b32_e32 v192, 16, v193
	v_and_b32_e32 v193, 0xffff0000, v193
	v_pk_fma_f32 v[128:129], v[128:129], 0.5, v[192:193] op_sel_hi:[1,0,1]
	v_lshlrev_b32_e32 v192, 16, v194
	v_and_b32_e32 v193, 0xffff0000, v194
	v_pk_fma_f32 v[126:127], v[126:127], 0.5, v[200:201] op_sel_hi:[1,0,1]
	v_pk_fma_f32 v[192:193], v[122:123], 0.5, v[192:193] op_sel_hi:[1,0,1]
	v_lshlrev_b32_e32 v122, 16, v195
	v_and_b32_e32 v123, 0xffff0000, v195
	v_pk_fma_f32 v[194:195], v[124:125], 0.5, v[122:123] op_sel_hi:[1,0,1]
	v_cvt_pk_bf16_f32 v122, v126, v127
	v_lshl_add_u64 v[126:127], s[50:51], 0, v[198:199]
	v_cvt_pk_bf16_f32 v123, v128, v129
	v_cvt_pk_bf16_f32 v124, v192, v193
	v_cvt_pk_bf16_f32 v125, v194, v195
	v_lshl_add_u64 v[126:127], v[126:127], 0, v[196:197]
	global_store_dwordx4 v[126:127], v[122:125], off
	v_lshlrev_b32_e32 v128, 16, v122
	v_lshlrev_b32_e32 v129, 16, v123
	v_and_b32_e32 v122, 0xffff0000, v122
	v_mul_f32_e32 v194, v122, v122
	v_fmac_f32_e32 v194, v128, v128
	v_and_b32_e32 v123, 0xffff0000, v123
	v_fmac_f32_e32 v194, v129, v129
	v_lshlrev_b32_e32 v192, 16, v124
	v_fmac_f32_e32 v194, v123, v123
	v_lshlrev_b32_e32 v122, 16, v154
	v_and_b32_e32 v123, 0xffff0000, v154
	v_and_b32_e32 v124, 0xffff0000, v124
	v_fmac_f32_e32 v194, v192, v192
	v_pk_fma_f32 v[118:119], v[118:119], 0.5, v[122:123] op_sel_hi:[1,0,1]
	v_lshlrev_b32_e32 v122, 16, v155
	v_and_b32_e32 v123, 0xffff0000, v155
	v_lshlrev_b32_e32 v193, 16, v125
	v_fmac_f32_e32 v194, v124, v124
	v_pk_fma_f32 v[120:121], v[120:121], 0.5, v[122:123] op_sel_hi:[1,0,1]
	v_lshlrev_b32_e32 v122, 16, v156
	v_and_b32_e32 v123, 0xffff0000, v156
	v_and_b32_e32 v125, 0xffff0000, v125
	v_fmac_f32_e32 v194, v193, v193
	v_pk_fma_f32 v[122:123], v[114:115], 0.5, v[122:123] op_sel_hi:[1,0,1]
	v_lshlrev_b32_e32 v114, 16, v157
	v_and_b32_e32 v115, 0xffff0000, v157
	v_fmac_f32_e32 v194, v125, v125
	v_pk_fma_f32 v[124:125], v[116:117], 0.5, v[114:115] op_sel_hi:[1,0,1]
	v_cvt_pk_bf16_f32 v114, v118, v119
	v_cvt_pk_bf16_f32 v115, v120, v121
	v_cvt_pk_bf16_f32 v116, v122, v123
	v_cvt_pk_bf16_f32 v117, v124, v125
	v_lshlrev_b32_e32 v118, 16, v114
	global_store_dwordx4 v[126:127], v[114:117], off offset:256
	v_fmac_f32_e32 v194, v118, v118
	v_lshlrev_b32_e32 v119, 16, v115
	v_and_b32_e32 v114, 0xffff0000, v114
	v_fmac_f32_e32 v194, v114, v114
	v_and_b32_e32 v115, 0xffff0000, v115
	v_fmac_f32_e32 v194, v119, v119
	v_lshlrev_b32_e32 v120, 16, v116
	v_fmac_f32_e32 v194, v115, v115
	v_and_b32_e32 v116, 0xffff0000, v116
	v_fmac_f32_e32 v194, v120, v120
	v_lshlrev_b32_e32 v121, 16, v117
	v_fmac_f32_e32 v194, v116, v116
	v_and_b32_e32 v117, 0xffff0000, v117
	v_fmac_f32_e32 v194, v121, v121
	v_fmac_f32_e32 v194, v117, v117
	ds_bpermute_b32 v114, v190, v194
	s_waitcnt lgkmcnt(0)
	v_add_f32_e32 v114, v194, v114
	ds_bpermute_b32 v115, v191, v114
	s_and_saveexec_b64 s[70:71], vcc
	s_cbranch_execz .LBB0_434
	s_waitcnt lgkmcnt(0)
	v_add_f32_e32 v116, v114, v115
	s_lshl_b32 s22, s44, 2
	v_lshlrev_b64 v[114:115], 6, v[170:171]
	s_ashr_i32 s23, s22, 31
	v_lshl_add_u64 v[114:115], s[52:53], 0, v[114:115]
	v_lshl_add_u64 v[114:115], s[22:23], 2, v[114:115]
	s_lshl_b32 s48, s78, 2
	v_lshl_add_u64 v[114:115], v[114:115], 0, s[48:49]
	global_store_dword v[114:115], v116, off

.LBB0_440:
	s_or_b64 exec, exec, s[70:71]
	v_add_u32_e32 v106, 0x80, v170
	v_ashrrev_i32_e32 v107, 31, v106
	v_lshlrev_b64 v[112:113], 11, v[106:107]
	s_waitcnt lgkmcnt(0)
	v_lshl_add_u64 v[64:65], v[172:173], 0, v[112:113]
	v_mov_b32_e32 v108, v202
	v_mov_b32_e32 v109, v203
	v_mov_b32_e32 v110, v204
	v_mov_b32_e32 v111, v205
	v_mov_b32_e32 v88, v206
	v_mov_b32_e32 v89, v207
	v_mov_b32_e32 v90, v208
	v_mov_b32_e32 v91, v209
	v_add_u32_e32 v102, 0x90, v170
	v_ashrrev_i32_e32 v103, 31, v102
	v_add_u32_e32 v98, 0xa0, v170
	v_lshlrev_b64 v[104:105], 11, v[102:103]
	v_ashrrev_i32_e32 v99, 31, v98
	v_add_u32_e32 v92, 0xb0, v170
	v_lshl_add_u64 v[64:65], v[172:173], 0, v[104:105]
	v_lshlrev_b64 v[100:101], 11, v[98:99]
	v_ashrrev_i32_e32 v93, 31, v92
	v_mov_b32_e32 v84, v210
	v_mov_b32_e32 v85, v211
	v_mov_b32_e32 v86, v212
	v_mov_b32_e32 v87, v213
	v_mov_b32_e32 v80, v214
	v_mov_b32_e32 v81, v215
	v_mov_b32_e32 v82, v216
	v_mov_b32_e32 v83, v217
	v_lshl_add_u64 v[64:65], v[172:173], 0, v[100:101]
	v_lshlrev_b64 v[94:95], 11, v[92:93]
	v_mov_b32_e32 v76, v236
	v_mov_b32_e32 v77, v237
	v_mov_b32_e32 v78, v238
	v_mov_b32_e32 v79, v239
	v_mov_b32_e32 v72, v240
	v_mov_b32_e32 v73, v241
	v_mov_b32_e32 v74, v242
	v_mov_b32_e32 v75, v243
	v_lshl_add_u64 v[64:65], v[172:173], 0, v[94:95]
	v_mov_b32_e32 v68, v244
	v_mov_b32_e32 v69, v245
	v_mov_b32_e32 v70, v246
	v_mov_b32_e32 v71, v247
	s_nop 0
	v_mov_b32_e32 v64, v158
	v_mov_b32_e32 v65, v159
	v_mov_b32_e32 v66, v160
	v_mov_b32_e32 v67, v161
	v_lshlrev_b32_e32 v114, 16, v108
	v_and_b32_e32 v115, 0xffff0000, v108
	v_lshlrev_b32_e32 v108, 16, v109
	v_and_b32_e32 v109, 0xffff0000, v109
	v_pk_fma_f32 v[62:63], v[62:63], 0.5, v[108:109] op_sel_hi:[1,0,1]
	v_lshlrev_b32_e32 v108, 16, v110
	v_and_b32_e32 v109, 0xffff0000, v110
	v_pk_fma_f32 v[60:61], v[60:61], 0.5, v[114:115] op_sel_hi:[1,0,1]
	v_pk_fma_f32 v[108:109], v[56:57], 0.5, v[108:109] op_sel_hi:[1,0,1]
	v_lshlrev_b32_e32 v56, 16, v111
	v_and_b32_e32 v57, 0xffff0000, v111
	v_pk_fma_f32 v[110:111], v[58:59], 0.5, v[56:57] op_sel_hi:[1,0,1]
	v_cvt_pk_bf16_f32 v56, v60, v61
	v_lshl_add_u64 v[60:61], s[50:51], 0, v[112:113]
	v_cvt_pk_bf16_f32 v57, v62, v63
	v_cvt_pk_bf16_f32 v58, v108, v109
	v_cvt_pk_bf16_f32 v59, v110, v111
	v_lshl_add_u64 v[60:61], v[168:169], 1, v[60:61]
	global_store_dwordx4 v[60:61], v[56:59], off
	v_lshlrev_b32_e32 v62, 16, v56
	v_lshlrev_b32_e32 v63, 16, v57
	v_and_b32_e32 v56, 0xffff0000, v56
	v_mul_f32_e32 v110, v56, v56
	v_fmac_f32_e32 v110, v62, v62
	v_and_b32_e32 v57, 0xffff0000, v57
	v_fmac_f32_e32 v110, v63, v63
	v_lshlrev_b32_e32 v108, 16, v58
	v_fmac_f32_e32 v110, v57, v57
	v_lshlrev_b32_e32 v56, 16, v88
	v_and_b32_e32 v57, 0xffff0000, v88
	v_and_b32_e32 v58, 0xffff0000, v58
	v_fmac_f32_e32 v110, v108, v108
	v_pk_fma_f32 v[52:53], v[52:53], 0.5, v[56:57] op_sel_hi:[1,0,1]
	v_lshlrev_b32_e32 v56, 16, v89
	v_and_b32_e32 v57, 0xffff0000, v89
	v_lshlrev_b32_e32 v109, 16, v59
	v_fmac_f32_e32 v110, v58, v58
	v_pk_fma_f32 v[54:55], v[54:55], 0.5, v[56:57] op_sel_hi:[1,0,1]
	v_lshlrev_b32_e32 v56, 16, v90
	v_and_b32_e32 v57, 0xffff0000, v90
	v_and_b32_e32 v59, 0xffff0000, v59
	v_fmac_f32_e32 v110, v109, v109
	v_pk_fma_f32 v[56:57], v[48:49], 0.5, v[56:57] op_sel_hi:[1,0,1]
	v_lshlrev_b32_e32 v48, 16, v91
	v_and_b32_e32 v49, 0xffff0000, v91
	v_fmac_f32_e32 v110, v59, v59
	v_pk_fma_f32 v[58:59], v[50:51], 0.5, v[48:49] op_sel_hi:[1,0,1]
	v_cvt_pk_bf16_f32 v48, v52, v53
	v_cvt_pk_bf16_f32 v49, v54, v55
	v_cvt_pk_bf16_f32 v50, v56, v57
	v_cvt_pk_bf16_f32 v51, v58, v59
	v_lshlrev_b32_e32 v52, 16, v48
	global_store_dwordx4 v[60:61], v[48:51], off offset:256
	v_fmac_f32_e32 v110, v52, v52
	v_lshlrev_b32_e32 v53, 16, v49
	v_and_b32_e32 v48, 0xffff0000, v48
	v_fmac_f32_e32 v110, v48, v48
	v_and_b32_e32 v49, 0xffff0000, v49
	v_fmac_f32_e32 v110, v53, v53
	v_lshlrev_b32_e32 v54, 16, v50
	v_fmac_f32_e32 v110, v49, v49
	v_and_b32_e32 v50, 0xffff0000, v50
	v_fmac_f32_e32 v110, v54, v54
	v_lshlrev_b32_e32 v55, 16, v51
	v_fmac_f32_e32 v110, v50, v50
	v_and_b32_e32 v51, 0xffff0000, v51
	v_fmac_f32_e32 v110, v55, v55
	v_fmac_f32_e32 v110, v51, v51
	ds_bpermute_b32 v48, v190, v110
	s_waitcnt lgkmcnt(0)
	v_add_f32_e32 v48, v110, v48
	ds_bpermute_b32 v49, v191, v48
	s_and_saveexec_b64 s[70:71], vcc
	s_cbranch_execz .LBB0_442
	s_waitcnt lgkmcnt(0)
	v_add_f32_e32 v50, v48, v49
	s_lshl_b32 s22, s44, 2
	v_lshlrev_b64 v[48:49], 6, v[106:107]
	s_ashr_i32 s23, s22, 31
	v_lshl_add_u64 v[48:49], s[52:53], 0, v[48:49]
	v_lshl_add_u64 v[48:49], s[22:23], 2, v[48:49]
	s_lshl_b32 s48, s78, 2
	v_lshl_add_u64 v[48:49], v[48:49], 0, s[48:49]
	global_store_dword v[48:49], v50, off
.LBB0_442:
	s_or_b64 exec, exec, s[70:71]
	v_lshlrev_b32_e32 v48, 16, v84
	s_waitcnt lgkmcnt(0)
	v_and_b32_e32 v49, 0xffff0000, v84
	v_pk_fma_f32 v[44:45], v[44:45], 0.5, v[48:49] op_sel_hi:[1,0,1]
	v_lshlrev_b32_e32 v48, 16, v85
	v_and_b32_e32 v49, 0xffff0000, v85
	v_pk_fma_f32 v[46:47], v[46:47], 0.5, v[48:49] op_sel_hi:[1,0,1]
	v_lshlrev_b32_e32 v48, 16, v86
	v_and_b32_e32 v49, 0xffff0000, v86
	v_pk_fma_f32 v[48:49], v[40:41], 0.5, v[48:49] op_sel_hi:[1,0,1]
	v_lshlrev_b32_e32 v40, 16, v87
	v_and_b32_e32 v41, 0xffff0000, v87
	v_pk_fma_f32 v[50:51], v[42:43], 0.5, v[40:41] op_sel_hi:[1,0,1]
	v_cvt_pk_bf16_f32 v40, v44, v45
	v_and_b32_e32 v45, 0xffff0000, v40
	v_cvt_pk_bf16_f32 v41, v46, v47
	v_lshlrev_b32_e32 v44, 16, v40
	v_mul_f32_e32 v52, v45, v45
	v_lshlrev_b32_e32 v46, 16, v41
	v_fmac_f32_e32 v52, v44, v44
	v_cvt_pk_bf16_f32 v42, v48, v49
	v_and_b32_e32 v47, 0xffff0000, v41
	v_fmac_f32_e32 v52, v46, v46
	v_lshlrev_b32_e32 v44, 16, v80
	v_and_b32_e32 v45, 0xffff0000, v80
	v_lshlrev_b32_e32 v48, 16, v42
	v_fmac_f32_e32 v52, v47, v47
	v_pk_fma_f32 v[36:37], v[36:37], 0.5, v[44:45] op_sel_hi:[1,0,1]
	v_lshlrev_b32_e32 v44, 16, v81
	v_and_b32_e32 v45, 0xffff0000, v81
	v_cvt_pk_bf16_f32 v43, v50, v51
	v_and_b32_e32 v49, 0xffff0000, v42
	v_fmac_f32_e32 v52, v48, v48
	v_pk_fma_f32 v[38:39], v[38:39], 0.5, v[44:45] op_sel_hi:[1,0,1]
	v_lshlrev_b32_e32 v44, 16, v82
	v_and_b32_e32 v45, 0xffff0000, v82
	v_lshlrev_b32_e32 v50, 16, v43
	v_fmac_f32_e32 v52, v49, v49
	v_pk_fma_f32 v[32:33], v[32:33], 0.5, v[44:45] op_sel_hi:[1,0,1]
	v_lshlrev_b32_e32 v44, 16, v83
	v_and_b32_e32 v45, 0xffff0000, v83
	v_and_b32_e32 v51, 0xffff0000, v43
	v_fmac_f32_e32 v52, v50, v50
	v_pk_fma_f32 v[44:45], v[34:35], 0.5, v[44:45] op_sel_hi:[1,0,1]
	v_cvt_pk_bf16_f32 v34, v36, v37
	v_fmac_f32_e32 v52, v51, v51
	v_cvt_pk_bf16_f32 v36, v32, v33
	v_lshlrev_b32_e32 v32, 16, v34
	v_cvt_pk_bf16_f32 v35, v38, v39
	v_and_b32_e32 v33, 0xffff0000, v34
	v_fmac_f32_e32 v52, v32, v32
	v_lshlrev_b32_e32 v38, 16, v35
	v_fmac_f32_e32 v52, v33, v33
	v_and_b32_e32 v39, 0xffff0000, v35
	v_fmac_f32_e32 v52, v38, v38
	v_cvt_pk_bf16_f32 v37, v44, v45
	v_lshlrev_b32_e32 v44, 16, v36
	v_fmac_f32_e32 v52, v39, v39
	v_and_b32_e32 v45, 0xffff0000, v36
	v_fmac_f32_e32 v52, v44, v44
	v_lshlrev_b32_e32 v46, 16, v37
	v_fmac_f32_e32 v52, v45, v45
	v_and_b32_e32 v47, 0xffff0000, v37
	v_fmac_f32_e32 v52, v46, v46
	v_fmac_f32_e32 v52, v47, v47
	ds_bpermute_b32 v32, v190, v52
	v_lshl_add_u64 v[38:39], s[50:51], 0, v[104:105]
	v_lshl_add_u64 v[38:39], v[168:169], 1, v[38:39]
	global_store_dwordx4 v[38:39], v[40:43], off
	global_store_dwordx4 v[38:39], v[34:37], off offset:256
	s_waitcnt lgkmcnt(0)
	v_add_f32_e32 v32, v52, v32
	ds_bpermute_b32 v33, v191, v32
	s_and_saveexec_b64 s[70:71], vcc
	s_cbranch_execz .LBB0_444
	s_waitcnt lgkmcnt(0)
	v_add_f32_e32 v34, v32, v33
	s_lshl_b32 s22, s44, 2
	v_lshlrev_b64 v[32:33], 6, v[102:103]
	s_ashr_i32 s23, s22, 31
	v_lshl_add_u64 v[32:33], s[52:53], 0, v[32:33]
	v_lshl_add_u64 v[32:33], s[22:23], 2, v[32:33]
	s_lshl_b32 s48, s78, 2
	v_lshl_add_u64 v[32:33], v[32:33], 0, s[48:49]
	global_store_dword v[32:33], v34, off
.LBB0_444:
	s_or_b64 exec, exec, s[70:71]
	v_lshlrev_b32_e32 v32, 16, v76
	s_waitcnt lgkmcnt(0)
	v_and_b32_e32 v33, 0xffff0000, v76
	v_pk_fma_f32 v[28:29], v[28:29], 0.5, v[32:33] op_sel_hi:[1,0,1]
	v_lshlrev_b32_e32 v32, 16, v77
	v_and_b32_e32 v33, 0xffff0000, v77
	v_pk_fma_f32 v[30:31], v[30:31], 0.5, v[32:33] op_sel_hi:[1,0,1]
	v_lshlrev_b32_e32 v32, 16, v78
	v_and_b32_e32 v33, 0xffff0000, v78
	v_pk_fma_f32 v[32:33], v[24:25], 0.5, v[32:33] op_sel_hi:[1,0,1]
	v_lshlrev_b32_e32 v24, 16, v79
	v_and_b32_e32 v25, 0xffff0000, v79
	v_pk_fma_f32 v[34:35], v[26:27], 0.5, v[24:25] op_sel_hi:[1,0,1]
	v_cvt_pk_bf16_f32 v24, v28, v29
	v_and_b32_e32 v29, 0xffff0000, v24
	v_cvt_pk_bf16_f32 v25, v30, v31
	v_lshlrev_b32_e32 v28, 16, v24
	v_mul_f32_e32 v36, v29, v29
	v_lshlrev_b32_e32 v30, 16, v25
	v_fmac_f32_e32 v36, v28, v28
	v_cvt_pk_bf16_f32 v26, v32, v33
	v_and_b32_e32 v31, 0xffff0000, v25
	v_fmac_f32_e32 v36, v30, v30
	v_lshlrev_b32_e32 v28, 16, v72
	v_and_b32_e32 v29, 0xffff0000, v72
	v_lshlrev_b32_e32 v32, 16, v26
	v_fmac_f32_e32 v36, v31, v31
	v_pk_fma_f32 v[20:21], v[20:21], 0.5, v[28:29] op_sel_hi:[1,0,1]
	v_lshlrev_b32_e32 v28, 16, v73
	v_and_b32_e32 v29, 0xffff0000, v73
	v_cvt_pk_bf16_f32 v27, v34, v35
	v_and_b32_e32 v33, 0xffff0000, v26
	v_fmac_f32_e32 v36, v32, v32
	v_pk_fma_f32 v[22:23], v[22:23], 0.5, v[28:29] op_sel_hi:[1,0,1]
	v_lshlrev_b32_e32 v28, 16, v74
	v_and_b32_e32 v29, 0xffff0000, v74
	v_lshlrev_b32_e32 v34, 16, v27
	v_fmac_f32_e32 v36, v33, v33
	v_pk_fma_f32 v[16:17], v[16:17], 0.5, v[28:29] op_sel_hi:[1,0,1]
	v_lshlrev_b32_e32 v28, 16, v75
	v_and_b32_e32 v29, 0xffff0000, v75
	v_and_b32_e32 v35, 0xffff0000, v27
	v_fmac_f32_e32 v36, v34, v34
	v_pk_fma_f32 v[28:29], v[18:19], 0.5, v[28:29] op_sel_hi:[1,0,1]
	v_cvt_pk_bf16_f32 v18, v20, v21
	v_fmac_f32_e32 v36, v35, v35
	v_cvt_pk_bf16_f32 v20, v16, v17
	v_lshlrev_b32_e32 v16, 16, v18
	v_cvt_pk_bf16_f32 v19, v22, v23
	v_and_b32_e32 v17, 0xffff0000, v18
	v_fmac_f32_e32 v36, v16, v16
	v_lshlrev_b32_e32 v22, 16, v19
	v_fmac_f32_e32 v36, v17, v17
	v_and_b32_e32 v23, 0xffff0000, v19
	v_fmac_f32_e32 v36, v22, v22
	v_cvt_pk_bf16_f32 v21, v28, v29
	v_lshlrev_b32_e32 v28, 16, v20
	v_fmac_f32_e32 v36, v23, v23
	v_and_b32_e32 v29, 0xffff0000, v20
	v_fmac_f32_e32 v36, v28, v28
	v_lshlrev_b32_e32 v30, 16, v21
	v_fmac_f32_e32 v36, v29, v29
	v_and_b32_e32 v31, 0xffff0000, v21
	v_fmac_f32_e32 v36, v30, v30
	v_fmac_f32_e32 v36, v31, v31
	ds_bpermute_b32 v16, v190, v36
	v_lshl_add_u64 v[22:23], s[50:51], 0, v[100:101]
	v_lshl_add_u64 v[22:23], v[168:169], 1, v[22:23]
	global_store_dwordx4 v[22:23], v[24:27], off
	global_store_dwordx4 v[22:23], v[18:21], off offset:256
	s_waitcnt lgkmcnt(0)
	v_add_f32_e32 v16, v36, v16
	ds_bpermute_b32 v17, v191, v16
	s_and_saveexec_b64 s[70:71], vcc
	s_cbranch_execz .LBB0_446
	s_waitcnt lgkmcnt(0)
	v_add_f32_e32 v18, v16, v17
	s_lshl_b32 s22, s44, 2
	v_lshlrev_b64 v[16:17], 6, v[98:99]
	s_ashr_i32 s23, s22, 31
	v_lshl_add_u64 v[16:17], s[52:53], 0, v[16:17]
	v_lshl_add_u64 v[16:17], s[22:23], 2, v[16:17]
	s_lshl_b32 s48, s78, 2
	v_lshl_add_u64 v[16:17], v[16:17], 0, s[48:49]
	global_store_dword v[16:17], v18, off
.LBB0_446:
	s_or_b64 exec, exec, s[70:71]
	v_lshlrev_b32_e32 v16, 16, v68
	s_waitcnt lgkmcnt(0)
	v_and_b32_e32 v17, 0xffff0000, v68
	v_pk_fma_f32 v[12:13], v[12:13], 0.5, v[16:17] op_sel_hi:[1,0,1]
	v_lshlrev_b32_e32 v16, 16, v69
	v_and_b32_e32 v17, 0xffff0000, v69
	v_pk_fma_f32 v[14:15], v[14:15], 0.5, v[16:17] op_sel_hi:[1,0,1]
	v_lshlrev_b32_e32 v16, 16, v70
	v_and_b32_e32 v17, 0xffff0000, v70
	v_pk_fma_f32 v[16:17], v[8:9], 0.5, v[16:17] op_sel_hi:[1,0,1]
	v_lshlrev_b32_e32 v8, 16, v71
	v_and_b32_e32 v9, 0xffff0000, v71
	v_pk_fma_f32 v[18:19], v[10:11], 0.5, v[8:9] op_sel_hi:[1,0,1]
	v_cvt_pk_bf16_f32 v8, v12, v13
	v_and_b32_e32 v13, 0xffff0000, v8
	v_cvt_pk_bf16_f32 v9, v14, v15
	v_lshlrev_b32_e32 v12, 16, v8
	v_mul_f32_e32 v20, v13, v13
	v_lshlrev_b32_e32 v14, 16, v9
	v_fmac_f32_e32 v20, v12, v12
	v_cvt_pk_bf16_f32 v10, v16, v17
	v_and_b32_e32 v15, 0xffff0000, v9
	v_fmac_f32_e32 v20, v14, v14
	v_lshlrev_b32_e32 v12, 16, v64
	v_and_b32_e32 v13, 0xffff0000, v64
	v_lshlrev_b32_e32 v16, 16, v10
	v_fmac_f32_e32 v20, v15, v15
	v_pk_fma_f32 v[4:5], v[4:5], 0.5, v[12:13] op_sel_hi:[1,0,1]
	v_lshlrev_b32_e32 v12, 16, v65
	v_and_b32_e32 v13, 0xffff0000, v65
	v_cvt_pk_bf16_f32 v11, v18, v19
	v_and_b32_e32 v17, 0xffff0000, v10
	v_fmac_f32_e32 v20, v16, v16
	v_pk_fma_f32 v[6:7], v[6:7], 0.5, v[12:13] op_sel_hi:[1,0,1]
	v_lshlrev_b32_e32 v12, 16, v66
	v_and_b32_e32 v13, 0xffff0000, v66
	v_lshlrev_b32_e32 v18, 16, v11
	v_fmac_f32_e32 v20, v17, v17
	v_pk_fma_f32 v[0:1], v[0:1], 0.5, v[12:13] op_sel_hi:[1,0,1]
	v_lshlrev_b32_e32 v12, 16, v67
	v_and_b32_e32 v13, 0xffff0000, v67
	v_and_b32_e32 v19, 0xffff0000, v11
	v_fmac_f32_e32 v20, v18, v18
	v_pk_fma_f32 v[12:13], v[2:3], 0.5, v[12:13] op_sel_hi:[1,0,1]
	v_cvt_pk_bf16_f32 v2, v4, v5
	v_fmac_f32_e32 v20, v19, v19
	v_cvt_pk_bf16_f32 v4, v0, v1
	v_lshlrev_b32_e32 v0, 16, v2
	v_cvt_pk_bf16_f32 v3, v6, v7
	v_and_b32_e32 v1, 0xffff0000, v2
	v_fmac_f32_e32 v20, v0, v0
	v_lshlrev_b32_e32 v6, 16, v3
	v_fmac_f32_e32 v20, v1, v1
	v_and_b32_e32 v7, 0xffff0000, v3
	v_fmac_f32_e32 v20, v6, v6
	v_cvt_pk_bf16_f32 v5, v12, v13
	v_lshlrev_b32_e32 v12, 16, v4
	v_fmac_f32_e32 v20, v7, v7
	v_and_b32_e32 v13, 0xffff0000, v4
	v_fmac_f32_e32 v20, v12, v12
	v_lshlrev_b32_e32 v14, 16, v5
	v_fmac_f32_e32 v20, v13, v13
	v_and_b32_e32 v15, 0xffff0000, v5
	v_fmac_f32_e32 v20, v14, v14
	v_fmac_f32_e32 v20, v15, v15
	ds_bpermute_b32 v0, v190, v20
	v_lshl_add_u64 v[6:7], s[50:51], 0, v[94:95]
	v_lshl_add_u64 v[6:7], v[168:169], 1, v[6:7]
	global_store_dwordx4 v[6:7], v[8:11], off
	global_store_dwordx4 v[6:7], v[2:5], off offset:256
	s_waitcnt lgkmcnt(0)
	v_add_f32_e32 v0, v20, v0
	ds_bpermute_b32 v1, v191, v0
	s_and_saveexec_b64 s[70:71], vcc
	s_cbranch_execz .LBB0_448
	s_waitcnt lgkmcnt(0)
	v_add_f32_e32 v2, v0, v1
	s_lshl_b32 s22, s44, 2
	v_lshlrev_b64 v[0:1], 6, v[92:93]
	s_ashr_i32 s23, s22, 31
	v_lshl_add_u64 v[0:1], s[52:53], 0, v[0:1]
	v_lshl_add_u64 v[0:1], s[22:23], 2, v[0:1]
	s_lshl_b32 s48, s78, 2
	v_lshl_add_u64 v[0:1], v[0:1], 0, s[48:49]
	global_store_dword v[0:1], v2, off

.LBB0_1828:
	v_mov_b32_e32 v130, v186
	v_mov_b32_e32 v131, v187
	s_lshl_b32 s22, s35, 8
	s_add_i32 s22, s22, s80
	v_and_b32_e32 v132, 64, v225
	v_add_u32_e32 v170, s22, v131
	s_lshl_b32 s22, s44, 8
	v_xor_b32_e32 v131, 16, v225
	v_add_u32_e32 v132, 64, v132
	s_or_b32 s22, s22, s81
	v_cmp_lt_i32_e32 vcc, v131, v132
	v_lshl_add_u32 v168, v130, 3, s22
	v_ashrrev_i32_e32 v169, 31, v168
	v_cndmask_b32_e32 v131, v225, v131, vcc
	v_lshlrev_b32_e32 v190, 2, v131
	v_xor_b32_e32 v131, 32, v225
	v_cmp_lt_i32_e32 vcc, v131, v132
	v_lshlrev_b64 v[196:197], 1, v[168:169]
	v_ashrrev_i32_e32 v171, 31, v170
	v_cndmask_b32_e32 v131, v225, v131, vcc
	v_lshl_add_u64 v[172:173], s[50:51], 0, v[196:197]
	v_lshlrev_b64 v[198:199], 11, v[170:171]
	v_lshlrev_b32_e32 v191, 2, v131
	v_cmp_eq_u32_e32 vcc, 0, v130
	v_lshl_add_u64 v[130:131], v[172:173], 0, v[198:199]
	global_load_dwordx4 v[192:195], v[130:131], off
	global_load_dwordx4 v[154:157], v[130:131], off offset:256
	v_add_u32_e32 v182, 16, v170
	v_ashrrev_i32_e32 v183, 31, v182
	v_add_u32_e32 v178, 32, v170
	v_lshlrev_b64 v[184:185], 11, v[182:183]
	v_ashrrev_i32_e32 v179, 31, v178
	v_add_u32_e32 v174, 48, v170
	v_lshl_add_u64 v[130:131], v[172:173], 0, v[184:185]
	v_lshlrev_b64 v[180:181], 11, v[178:179]
	v_ashrrev_i32_e32 v175, 31, v174
	global_load_dwordx4 v[150:153], v[130:131], off
	global_load_dwordx4 v[146:149], v[130:131], off offset:256
	v_lshl_add_u64 v[130:131], v[172:173], 0, v[180:181]
	v_lshlrev_b64 v[176:177], 11, v[174:175]
	global_load_dwordx4 v[142:145], v[130:131], off
	global_load_dwordx4 v[138:141], v[130:131], off offset:256
	v_lshl_add_u64 v[130:131], v[172:173], 0, v[176:177]
	global_load_dwordx4 v[134:137], v[130:131], off
	s_nop 0
	global_load_dwordx4 v[130:133], v[130:131], off offset:256
	s_mov_b64 s[22:23], 0x40000
	v_lshl_add_u64 v[218:219], v[172:173], 0, v[198:199]
	v_lshl_add_u64 v[218:219], s[22:23], 0, v[218:219]
	global_load_dwordx4 v[202:205], v[218:219], off
	global_load_dwordx4 v[206:209], v[218:219], off offset:256
	v_lshl_add_u64 v[218:219], v[172:173], 0, v[184:185]
	v_lshl_add_u64 v[218:219], s[22:23], 0, v[218:219]
	global_load_dwordx4 v[210:213], v[218:219], off
	global_load_dwordx4 v[214:217], v[218:219], off offset:256
	v_lshl_add_u64 v[218:219], v[172:173], 0, v[180:181]
	v_lshl_add_u64 v[218:219], s[22:23], 0, v[218:219]
	global_load_dwordx4 v[236:239], v[218:219], off
	global_load_dwordx4 v[240:243], v[218:219], off offset:256
	v_lshl_add_u64 v[218:219], v[172:173], 0, v[176:177]
	v_lshl_add_u64 v[218:219], s[22:23], 0, v[218:219]
	global_load_dwordx4 v[244:247], v[218:219], off
	global_load_dwordx4 v[158:161], v[218:219], off offset:256
	s_waitcnt vmcnt(0)
	v_lshlrev_b32_e32 v200, 16, v192
	v_and_b32_e32 v201, 0xffff0000, v192
	v_lshlrev_b32_e32 v192, 16, v193
	v_and_b32_e32 v193, 0xffff0000, v193
	v_pk_add_f32 v[128:129], v[128:129], v[192:193]
	v_lshlrev_b32_e32 v192, 16, v194
	v_and_b32_e32 v193, 0xffff0000, v194
	v_pk_add_f32 v[126:127], v[126:127], v[200:201]
	v_pk_add_f32 v[192:193], v[122:123], v[192:193]
	v_lshlrev_b32_e32 v122, 16, v195
	v_and_b32_e32 v123, 0xffff0000, v195
	v_pk_add_f32 v[194:195], v[124:125], v[122:123]
	v_cvt_pk_bf16_f32 v122, v126, v127
	v_lshl_add_u64 v[126:127], s[50:51], 0, v[198:199]
	v_cvt_pk_bf16_f32 v123, v128, v129
	v_cvt_pk_bf16_f32 v124, v192, v193
	v_cvt_pk_bf16_f32 v125, v194, v195
	v_lshl_add_u64 v[126:127], v[126:127], 0, v[196:197]
	global_store_dwordx4 v[126:127], v[122:125], off
	v_lshlrev_b32_e32 v128, 16, v122
	v_lshlrev_b32_e32 v129, 16, v123
	v_and_b32_e32 v122, 0xffff0000, v122
	v_mul_f32_e32 v194, v122, v122
	v_fmac_f32_e32 v194, v128, v128
	v_and_b32_e32 v123, 0xffff0000, v123
	v_fmac_f32_e32 v194, v129, v129
	v_lshlrev_b32_e32 v192, 16, v124
	v_fmac_f32_e32 v194, v123, v123
	v_lshlrev_b32_e32 v122, 16, v154
	v_and_b32_e32 v123, 0xffff0000, v154
	v_and_b32_e32 v124, 0xffff0000, v124
	v_fmac_f32_e32 v194, v192, v192
	v_pk_add_f32 v[118:119], v[118:119], v[122:123]
	v_lshlrev_b32_e32 v122, 16, v155
	v_and_b32_e32 v123, 0xffff0000, v155
	v_lshlrev_b32_e32 v193, 16, v125
	v_fmac_f32_e32 v194, v124, v124
	v_pk_add_f32 v[120:121], v[120:121], v[122:123]
	v_lshlrev_b32_e32 v122, 16, v156
	v_and_b32_e32 v123, 0xffff0000, v156
	v_and_b32_e32 v125, 0xffff0000, v125
	v_fmac_f32_e32 v194, v193, v193
	v_pk_add_f32 v[122:123], v[114:115], v[122:123]
	v_lshlrev_b32_e32 v114, 16, v157
	v_and_b32_e32 v115, 0xffff0000, v157
	v_fmac_f32_e32 v194, v125, v125
	v_pk_add_f32 v[124:125], v[116:117], v[114:115]
	v_cvt_pk_bf16_f32 v114, v118, v119
	v_cvt_pk_bf16_f32 v115, v120, v121
	v_cvt_pk_bf16_f32 v116, v122, v123
	v_cvt_pk_bf16_f32 v117, v124, v125
	v_lshlrev_b32_e32 v118, 16, v114
	global_store_dwordx4 v[126:127], v[114:117], off offset:256
	v_fmac_f32_e32 v194, v118, v118
	v_lshlrev_b32_e32 v119, 16, v115
	v_and_b32_e32 v114, 0xffff0000, v114
	v_fmac_f32_e32 v194, v114, v114
	v_and_b32_e32 v115, 0xffff0000, v115
	v_fmac_f32_e32 v194, v119, v119
	v_lshlrev_b32_e32 v120, 16, v116
	v_fmac_f32_e32 v194, v115, v115
	v_and_b32_e32 v116, 0xffff0000, v116
	v_fmac_f32_e32 v194, v120, v120
	v_lshlrev_b32_e32 v121, 16, v117
	v_fmac_f32_e32 v194, v116, v116
	v_and_b32_e32 v117, 0xffff0000, v117
	v_fmac_f32_e32 v194, v121, v121
	v_fmac_f32_e32 v194, v117, v117
	ds_bpermute_b32 v114, v190, v194
	s_waitcnt lgkmcnt(0)
	v_add_f32_e32 v114, v194, v114
	ds_bpermute_b32 v115, v191, v114
	s_and_saveexec_b64 s[70:71], vcc
	s_cbranch_execz .LBB0_1830
	s_waitcnt lgkmcnt(0)
	v_add_f32_e32 v116, v114, v115
	s_lshl_b32 s22, s44, 2
	v_lshlrev_b64 v[114:115], 6, v[170:171]
	s_ashr_i32 s23, s22, 31
	v_lshl_add_u64 v[114:115], s[52:53], 0, v[114:115]
	v_lshl_add_u64 v[114:115], s[22:23], 2, v[114:115]
	s_lshl_b32 s48, s78, 2
	v_lshl_add_u64 v[114:115], v[114:115], 0, s[48:49]
	global_store_dword v[114:115], v116, off

.LBB0_1836:
	s_or_b64 exec, exec, s[70:71]
	v_add_u32_e32 v106, 0x80, v170
	v_ashrrev_i32_e32 v107, 31, v106
	v_lshlrev_b64 v[112:113], 11, v[106:107]
	s_waitcnt lgkmcnt(0)
	v_lshl_add_u64 v[64:65], v[172:173], 0, v[112:113]
	v_mov_b32_e32 v108, v202
	v_mov_b32_e32 v109, v203
	v_mov_b32_e32 v110, v204
	v_mov_b32_e32 v111, v205
	v_mov_b32_e32 v88, v206
	v_mov_b32_e32 v89, v207
	v_mov_b32_e32 v90, v208
	v_mov_b32_e32 v91, v209
	v_add_u32_e32 v102, 0x90, v170
	v_ashrrev_i32_e32 v103, 31, v102
	v_add_u32_e32 v98, 0xa0, v170
	v_lshlrev_b64 v[104:105], 11, v[102:103]
	v_ashrrev_i32_e32 v99, 31, v98
	v_add_u32_e32 v92, 0xb0, v170
	v_lshl_add_u64 v[64:65], v[172:173], 0, v[104:105]
	v_lshlrev_b64 v[100:101], 11, v[98:99]
	v_ashrrev_i32_e32 v93, 31, v92
	v_mov_b32_e32 v84, v210
	v_mov_b32_e32 v85, v211
	v_mov_b32_e32 v86, v212
	v_mov_b32_e32 v87, v213
	v_mov_b32_e32 v80, v214
	v_mov_b32_e32 v81, v215
	v_mov_b32_e32 v82, v216
	v_mov_b32_e32 v83, v217
	v_lshl_add_u64 v[64:65], v[172:173], 0, v[100:101]
	v_lshlrev_b64 v[94:95], 11, v[92:93]
	v_mov_b32_e32 v76, v236
	v_mov_b32_e32 v77, v237
	v_mov_b32_e32 v78, v238
	v_mov_b32_e32 v79, v239
	v_mov_b32_e32 v72, v240
	v_mov_b32_e32 v73, v241
	v_mov_b32_e32 v74, v242
	v_mov_b32_e32 v75, v243
	v_lshl_add_u64 v[64:65], v[172:173], 0, v[94:95]
	v_mov_b32_e32 v68, v244
	v_mov_b32_e32 v69, v245
	v_mov_b32_e32 v70, v246
	v_mov_b32_e32 v71, v247
	s_nop 0
	v_mov_b32_e32 v64, v158
	v_mov_b32_e32 v65, v159
	v_mov_b32_e32 v66, v160
	v_mov_b32_e32 v67, v161
	v_lshlrev_b32_e32 v114, 16, v108
	v_and_b32_e32 v115, 0xffff0000, v108
	v_lshlrev_b32_e32 v108, 16, v109
	v_and_b32_e32 v109, 0xffff0000, v109
	v_pk_add_f32 v[62:63], v[62:63], v[108:109]
	v_lshlrev_b32_e32 v108, 16, v110
	v_and_b32_e32 v109, 0xffff0000, v110
	v_pk_add_f32 v[60:61], v[60:61], v[114:115]
	v_pk_add_f32 v[108:109], v[56:57], v[108:109]
	v_lshlrev_b32_e32 v56, 16, v111
	v_and_b32_e32 v57, 0xffff0000, v111
	v_pk_add_f32 v[110:111], v[58:59], v[56:57]
	v_cvt_pk_bf16_f32 v56, v60, v61
	v_lshl_add_u64 v[60:61], s[50:51], 0, v[112:113]
	v_cvt_pk_bf16_f32 v57, v62, v63
	v_cvt_pk_bf16_f32 v58, v108, v109
	v_cvt_pk_bf16_f32 v59, v110, v111
	v_lshl_add_u64 v[60:61], v[168:169], 1, v[60:61]
	global_store_dwordx4 v[60:61], v[56:59], off
	v_lshlrev_b32_e32 v62, 16, v56
	v_lshlrev_b32_e32 v63, 16, v57
	v_and_b32_e32 v56, 0xffff0000, v56
	v_mul_f32_e32 v110, v56, v56
	v_fmac_f32_e32 v110, v62, v62
	v_and_b32_e32 v57, 0xffff0000, v57
	v_fmac_f32_e32 v110, v63, v63
	v_lshlrev_b32_e32 v108, 16, v58
	v_fmac_f32_e32 v110, v57, v57
	v_lshlrev_b32_e32 v56, 16, v88
	v_and_b32_e32 v57, 0xffff0000, v88
	v_and_b32_e32 v58, 0xffff0000, v58
	v_fmac_f32_e32 v110, v108, v108
	v_pk_add_f32 v[52:53], v[52:53], v[56:57]
	v_lshlrev_b32_e32 v56, 16, v89
	v_and_b32_e32 v57, 0xffff0000, v89
	v_lshlrev_b32_e32 v109, 16, v59
	v_fmac_f32_e32 v110, v58, v58
	v_pk_add_f32 v[54:55], v[54:55], v[56:57]
	v_lshlrev_b32_e32 v56, 16, v90
	v_and_b32_e32 v57, 0xffff0000, v90
	v_and_b32_e32 v59, 0xffff0000, v59
	v_fmac_f32_e32 v110, v109, v109
	v_pk_add_f32 v[56:57], v[48:49], v[56:57]
	v_lshlrev_b32_e32 v48, 16, v91
	v_and_b32_e32 v49, 0xffff0000, v91
	v_fmac_f32_e32 v110, v59, v59
	v_pk_add_f32 v[58:59], v[50:51], v[48:49]
	v_cvt_pk_bf16_f32 v48, v52, v53
	v_cvt_pk_bf16_f32 v49, v54, v55
	v_cvt_pk_bf16_f32 v50, v56, v57
	v_cvt_pk_bf16_f32 v51, v58, v59
	v_lshlrev_b32_e32 v52, 16, v48
	global_store_dwordx4 v[60:61], v[48:51], off offset:256
	v_fmac_f32_e32 v110, v52, v52
	v_lshlrev_b32_e32 v53, 16, v49
	v_and_b32_e32 v48, 0xffff0000, v48
	v_fmac_f32_e32 v110, v48, v48
	v_and_b32_e32 v49, 0xffff0000, v49
	v_fmac_f32_e32 v110, v53, v53
	v_lshlrev_b32_e32 v54, 16, v50
	v_fmac_f32_e32 v110, v49, v49
	v_and_b32_e32 v50, 0xffff0000, v50
	v_fmac_f32_e32 v110, v54, v54
	v_lshlrev_b32_e32 v55, 16, v51
	v_fmac_f32_e32 v110, v50, v50
	v_and_b32_e32 v51, 0xffff0000, v51
	v_fmac_f32_e32 v110, v55, v55
	v_fmac_f32_e32 v110, v51, v51
	ds_bpermute_b32 v48, v190, v110
	s_waitcnt lgkmcnt(0)
	v_add_f32_e32 v48, v110, v48
	ds_bpermute_b32 v49, v191, v48
	s_and_saveexec_b64 s[70:71], vcc
	s_cbranch_execz .LBB0_1838
	s_waitcnt lgkmcnt(0)
	v_add_f32_e32 v50, v48, v49
	s_lshl_b32 s22, s44, 2
	v_lshlrev_b64 v[48:49], 6, v[106:107]
	s_ashr_i32 s23, s22, 31
	v_lshl_add_u64 v[48:49], s[52:53], 0, v[48:49]
	v_lshl_add_u64 v[48:49], s[22:23], 2, v[48:49]
	s_lshl_b32 s48, s78, 2
	v_lshl_add_u64 v[48:49], v[48:49], 0, s[48:49]
	global_store_dword v[48:49], v50, off
.LBB0_1838:
	s_or_b64 exec, exec, s[70:71]
	v_lshlrev_b32_e32 v48, 16, v84
	s_waitcnt lgkmcnt(0)
	v_and_b32_e32 v49, 0xffff0000, v84
	v_pk_add_f32 v[44:45], v[44:45], v[48:49]
	v_lshlrev_b32_e32 v48, 16, v85
	v_and_b32_e32 v49, 0xffff0000, v85
	v_pk_add_f32 v[46:47], v[46:47], v[48:49]
	v_lshlrev_b32_e32 v48, 16, v86
	v_and_b32_e32 v49, 0xffff0000, v86
	v_pk_add_f32 v[48:49], v[40:41], v[48:49]
	v_lshlrev_b32_e32 v40, 16, v87
	v_and_b32_e32 v41, 0xffff0000, v87
	v_pk_add_f32 v[50:51], v[42:43], v[40:41]
	v_cvt_pk_bf16_f32 v40, v44, v45
	v_and_b32_e32 v45, 0xffff0000, v40
	v_cvt_pk_bf16_f32 v41, v46, v47
	v_lshlrev_b32_e32 v44, 16, v40
	v_mul_f32_e32 v52, v45, v45
	v_lshlrev_b32_e32 v46, 16, v41
	v_fmac_f32_e32 v52, v44, v44
	v_cvt_pk_bf16_f32 v42, v48, v49
	v_and_b32_e32 v47, 0xffff0000, v41
	v_fmac_f32_e32 v52, v46, v46
	v_lshlrev_b32_e32 v44, 16, v80
	v_and_b32_e32 v45, 0xffff0000, v80
	v_lshlrev_b32_e32 v48, 16, v42
	v_fmac_f32_e32 v52, v47, v47
	v_pk_add_f32 v[36:37], v[36:37], v[44:45]
	v_lshlrev_b32_e32 v44, 16, v81
	v_and_b32_e32 v45, 0xffff0000, v81
	v_cvt_pk_bf16_f32 v43, v50, v51
	v_and_b32_e32 v49, 0xffff0000, v42
	v_fmac_f32_e32 v52, v48, v48
	v_pk_add_f32 v[38:39], v[38:39], v[44:45]
	v_lshlrev_b32_e32 v44, 16, v82
	v_and_b32_e32 v45, 0xffff0000, v82
	v_lshlrev_b32_e32 v50, 16, v43
	v_fmac_f32_e32 v52, v49, v49
	v_pk_add_f32 v[32:33], v[32:33], v[44:45]
	v_lshlrev_b32_e32 v44, 16, v83
	v_and_b32_e32 v45, 0xffff0000, v83
	v_and_b32_e32 v51, 0xffff0000, v43
	v_fmac_f32_e32 v52, v50, v50
	v_pk_add_f32 v[44:45], v[34:35], v[44:45]
	v_cvt_pk_bf16_f32 v34, v36, v37
	v_fmac_f32_e32 v52, v51, v51
	v_cvt_pk_bf16_f32 v36, v32, v33
	v_lshlrev_b32_e32 v32, 16, v34
	v_cvt_pk_bf16_f32 v35, v38, v39
	v_and_b32_e32 v33, 0xffff0000, v34
	v_fmac_f32_e32 v52, v32, v32
	v_lshlrev_b32_e32 v38, 16, v35
	v_fmac_f32_e32 v52, v33, v33
	v_and_b32_e32 v39, 0xffff0000, v35
	v_fmac_f32_e32 v52, v38, v38
	v_cvt_pk_bf16_f32 v37, v44, v45
	v_lshlrev_b32_e32 v44, 16, v36
	v_fmac_f32_e32 v52, v39, v39
	v_and_b32_e32 v45, 0xffff0000, v36
	v_fmac_f32_e32 v52, v44, v44
	v_lshlrev_b32_e32 v46, 16, v37
	v_fmac_f32_e32 v52, v45, v45
	v_and_b32_e32 v47, 0xffff0000, v37
	v_fmac_f32_e32 v52, v46, v46
	v_fmac_f32_e32 v52, v47, v47
	ds_bpermute_b32 v32, v190, v52
	v_lshl_add_u64 v[38:39], s[50:51], 0, v[104:105]
	v_lshl_add_u64 v[38:39], v[168:169], 1, v[38:39]
	global_store_dwordx4 v[38:39], v[40:43], off
	global_store_dwordx4 v[38:39], v[34:37], off offset:256
	s_waitcnt lgkmcnt(0)
	v_add_f32_e32 v32, v52, v32
	ds_bpermute_b32 v33, v191, v32
	s_and_saveexec_b64 s[70:71], vcc
	s_cbranch_execz .LBB0_1840
	s_waitcnt lgkmcnt(0)
	v_add_f32_e32 v34, v32, v33
	s_lshl_b32 s22, s44, 2
	v_lshlrev_b64 v[32:33], 6, v[102:103]
	s_ashr_i32 s23, s22, 31
	v_lshl_add_u64 v[32:33], s[52:53], 0, v[32:33]
	v_lshl_add_u64 v[32:33], s[22:23], 2, v[32:33]
	s_lshl_b32 s48, s78, 2
	v_lshl_add_u64 v[32:33], v[32:33], 0, s[48:49]
	global_store_dword v[32:33], v34, off
.LBB0_1840:
	s_or_b64 exec, exec, s[70:71]
	v_lshlrev_b32_e32 v32, 16, v76
	s_waitcnt lgkmcnt(0)
	v_and_b32_e32 v33, 0xffff0000, v76
	v_pk_add_f32 v[28:29], v[28:29], v[32:33]
	v_lshlrev_b32_e32 v32, 16, v77
	v_and_b32_e32 v33, 0xffff0000, v77
	v_pk_add_f32 v[30:31], v[30:31], v[32:33]
	v_lshlrev_b32_e32 v32, 16, v78
	v_and_b32_e32 v33, 0xffff0000, v78
	v_pk_add_f32 v[32:33], v[24:25], v[32:33]
	v_lshlrev_b32_e32 v24, 16, v79
	v_and_b32_e32 v25, 0xffff0000, v79
	v_pk_add_f32 v[34:35], v[26:27], v[24:25]
	v_cvt_pk_bf16_f32 v24, v28, v29
	v_and_b32_e32 v29, 0xffff0000, v24
	v_cvt_pk_bf16_f32 v25, v30, v31
	v_lshlrev_b32_e32 v28, 16, v24
	v_mul_f32_e32 v36, v29, v29
	v_lshlrev_b32_e32 v30, 16, v25
	v_fmac_f32_e32 v36, v28, v28
	v_cvt_pk_bf16_f32 v26, v32, v33
	v_and_b32_e32 v31, 0xffff0000, v25
	v_fmac_f32_e32 v36, v30, v30
	v_lshlrev_b32_e32 v28, 16, v72
	v_and_b32_e32 v29, 0xffff0000, v72
	v_lshlrev_b32_e32 v32, 16, v26
	v_fmac_f32_e32 v36, v31, v31
	v_pk_add_f32 v[20:21], v[20:21], v[28:29]
	v_lshlrev_b32_e32 v28, 16, v73
	v_and_b32_e32 v29, 0xffff0000, v73
	v_cvt_pk_bf16_f32 v27, v34, v35
	v_and_b32_e32 v33, 0xffff0000, v26
	v_fmac_f32_e32 v36, v32, v32
	v_pk_add_f32 v[22:23], v[22:23], v[28:29]
	v_lshlrev_b32_e32 v28, 16, v74
	v_and_b32_e32 v29, 0xffff0000, v74
	v_lshlrev_b32_e32 v34, 16, v27
	v_fmac_f32_e32 v36, v33, v33
	v_pk_add_f32 v[16:17], v[16:17], v[28:29]
	v_lshlrev_b32_e32 v28, 16, v75
	v_and_b32_e32 v29, 0xffff0000, v75
	v_and_b32_e32 v35, 0xffff0000, v27
	v_fmac_f32_e32 v36, v34, v34
	v_pk_add_f32 v[28:29], v[18:19], v[28:29]
	v_cvt_pk_bf16_f32 v18, v20, v21
	v_fmac_f32_e32 v36, v35, v35
	v_cvt_pk_bf16_f32 v20, v16, v17
	v_lshlrev_b32_e32 v16, 16, v18
	v_cvt_pk_bf16_f32 v19, v22, v23
	v_and_b32_e32 v17, 0xffff0000, v18
	v_fmac_f32_e32 v36, v16, v16
	v_lshlrev_b32_e32 v22, 16, v19
	v_fmac_f32_e32 v36, v17, v17
	v_and_b32_e32 v23, 0xffff0000, v19
	v_fmac_f32_e32 v36, v22, v22
	v_cvt_pk_bf16_f32 v21, v28, v29
	v_lshlrev_b32_e32 v28, 16, v20
	v_fmac_f32_e32 v36, v23, v23
	v_and_b32_e32 v29, 0xffff0000, v20
	v_fmac_f32_e32 v36, v28, v28
	v_lshlrev_b32_e32 v30, 16, v21
	v_fmac_f32_e32 v36, v29, v29
	v_and_b32_e32 v31, 0xffff0000, v21
	v_fmac_f32_e32 v36, v30, v30
	v_fmac_f32_e32 v36, v31, v31
	ds_bpermute_b32 v16, v190, v36
	v_lshl_add_u64 v[22:23], s[50:51], 0, v[100:101]
	v_lshl_add_u64 v[22:23], v[168:169], 1, v[22:23]
	global_store_dwordx4 v[22:23], v[24:27], off
	global_store_dwordx4 v[22:23], v[18:21], off offset:256
	s_waitcnt lgkmcnt(0)
	v_add_f32_e32 v16, v36, v16
	ds_bpermute_b32 v17, v191, v16
	s_and_saveexec_b64 s[70:71], vcc
	s_cbranch_execz .LBB0_1842
	s_waitcnt lgkmcnt(0)
	v_add_f32_e32 v18, v16, v17
	s_lshl_b32 s22, s44, 2
	v_lshlrev_b64 v[16:17], 6, v[98:99]
	s_ashr_i32 s23, s22, 31
	v_lshl_add_u64 v[16:17], s[52:53], 0, v[16:17]
	v_lshl_add_u64 v[16:17], s[22:23], 2, v[16:17]
	s_lshl_b32 s48, s78, 2
	v_lshl_add_u64 v[16:17], v[16:17], 0, s[48:49]
	global_store_dword v[16:17], v18, off
.LBB0_1842:
	s_or_b64 exec, exec, s[70:71]
	v_lshlrev_b32_e32 v16, 16, v68
	s_waitcnt lgkmcnt(0)
	v_and_b32_e32 v17, 0xffff0000, v68
	v_pk_add_f32 v[12:13], v[12:13], v[16:17]
	v_lshlrev_b32_e32 v16, 16, v69
	v_and_b32_e32 v17, 0xffff0000, v69
	v_pk_add_f32 v[14:15], v[14:15], v[16:17]
	v_lshlrev_b32_e32 v16, 16, v70
	v_and_b32_e32 v17, 0xffff0000, v70
	v_pk_add_f32 v[16:17], v[8:9], v[16:17]
	v_lshlrev_b32_e32 v8, 16, v71
	v_and_b32_e32 v9, 0xffff0000, v71
	v_pk_add_f32 v[18:19], v[10:11], v[8:9]
	v_cvt_pk_bf16_f32 v8, v12, v13
	v_and_b32_e32 v13, 0xffff0000, v8
	v_cvt_pk_bf16_f32 v9, v14, v15
	v_lshlrev_b32_e32 v12, 16, v8
	v_mul_f32_e32 v20, v13, v13
	v_lshlrev_b32_e32 v14, 16, v9
	v_fmac_f32_e32 v20, v12, v12
	v_cvt_pk_bf16_f32 v10, v16, v17
	v_and_b32_e32 v15, 0xffff0000, v9
	v_fmac_f32_e32 v20, v14, v14
	v_lshlrev_b32_e32 v12, 16, v64
	v_and_b32_e32 v13, 0xffff0000, v64
	v_lshlrev_b32_e32 v16, 16, v10
	v_fmac_f32_e32 v20, v15, v15
	v_pk_add_f32 v[4:5], v[4:5], v[12:13]
	v_lshlrev_b32_e32 v12, 16, v65
	v_and_b32_e32 v13, 0xffff0000, v65
	v_cvt_pk_bf16_f32 v11, v18, v19
	v_and_b32_e32 v17, 0xffff0000, v10
	v_fmac_f32_e32 v20, v16, v16
	v_pk_add_f32 v[6:7], v[6:7], v[12:13]
	v_lshlrev_b32_e32 v12, 16, v66
	v_and_b32_e32 v13, 0xffff0000, v66
	v_lshlrev_b32_e32 v18, 16, v11
	v_fmac_f32_e32 v20, v17, v17
	v_pk_add_f32 v[0:1], v[0:1], v[12:13]
	v_lshlrev_b32_e32 v12, 16, v67
	v_and_b32_e32 v13, 0xffff0000, v67
	v_and_b32_e32 v19, 0xffff0000, v11
	v_fmac_f32_e32 v20, v18, v18
	v_pk_add_f32 v[12:13], v[2:3], v[12:13]
	v_cvt_pk_bf16_f32 v2, v4, v5
	v_fmac_f32_e32 v20, v19, v19
	v_cvt_pk_bf16_f32 v4, v0, v1
	v_lshlrev_b32_e32 v0, 16, v2
	v_cvt_pk_bf16_f32 v3, v6, v7
	v_and_b32_e32 v1, 0xffff0000, v2
	v_fmac_f32_e32 v20, v0, v0
	v_lshlrev_b32_e32 v6, 16, v3
	v_fmac_f32_e32 v20, v1, v1
	v_and_b32_e32 v7, 0xffff0000, v3
	v_fmac_f32_e32 v20, v6, v6
	v_cvt_pk_bf16_f32 v5, v12, v13
	v_lshlrev_b32_e32 v12, 16, v4
	v_fmac_f32_e32 v20, v7, v7
	v_and_b32_e32 v13, 0xffff0000, v4
	v_fmac_f32_e32 v20, v12, v12
	v_lshlrev_b32_e32 v14, 16, v5
	v_fmac_f32_e32 v20, v13, v13
	v_and_b32_e32 v15, 0xffff0000, v5
	v_fmac_f32_e32 v20, v14, v14
	v_fmac_f32_e32 v20, v15, v15
	ds_bpermute_b32 v0, v190, v20
	v_lshl_add_u64 v[6:7], s[50:51], 0, v[94:95]
	v_lshl_add_u64 v[6:7], v[168:169], 1, v[6:7]
	global_store_dwordx4 v[6:7], v[8:11], off
	global_store_dwordx4 v[6:7], v[2:5], off offset:256
	s_waitcnt lgkmcnt(0)
	v_add_f32_e32 v0, v20, v0
	ds_bpermute_b32 v1, v191, v0
	s_and_saveexec_b64 s[70:71], vcc
	s_cbranch_execz .LBB0_1844
	s_waitcnt lgkmcnt(0)
	v_add_f32_e32 v2, v0, v1
	s_lshl_b32 s22, s44, 2
	v_lshlrev_b64 v[0:1], 6, v[92:93]
	s_ashr_i32 s23, s22, 31
	v_lshl_add_u64 v[0:1], s[52:53], 0, v[0:1]
	v_lshl_add_u64 v[0:1], s[22:23], 2, v[0:1]
	s_lshl_b32 s48, s78, 2
	v_lshl_add_u64 v[0:1], v[0:1], 0, s[48:49]
	global_store_dword v[0:1], v2, off
